# HGRN A/B state-update v_pk_mul_f32 split into scalar v_mul only (no ds_read2 split), on top of v23
# baseline (speedup 1.0000x reference)
; #define MFMA16(a, b, c) __builtin_amdgcn_mfma_f32_16x16x32_bf16((a), (b), (c), 0, 0, 0)
; __device__ __forceinline__ bf16x8 pack8(f32x4 a, f32x4 b) { u32x4 w = {pk2(a[0], a[1]), pk2(a[2], a[3]), pk2(b[0], b[1]), pk2(b[2], b[3])}; return __builtin_bit_cast(bf16x8, w); }
; __device__ __forceinline__ bf16x8 cat8(bf16x4 lo, bf16x4 hi) { return __builtin_shufflevector(lo, hi, 0, 1, 2, 3, 4, 5, 6, 7); }
; __device__ __forceinline__ void hgrn_b(unsigned char* lds, const Params& p, int jl, const bf16_t* proj, bf16_t* mix, const float* dbuf, const bf16_t* scr, const float* useg, const float* dseg, int blk, int G, int tid) {
;     ...
;             const bf16_t* qh = QH + buf * (64 * 136); const bf16_t* kt = KT + buf * (128 * 72); const bf16_t* vt = VT + buf * (128 * 72); const float* dl = DL + buf * 128;
;             f32x4 oT[4];
;             { bf16x8 sa[4];
; #pragma unroll
;               for (int k2 = 0; k2 < 4; ++k2) sa[k2] = pack8(S[2 * k2], S[2 * k2 + 1]);
; #pragma unroll
;               for (int th = 0; th < 2; ++th) { bf16x8 qfr[2][4];
; #pragma unroll
;                   for (int t2 = 0; t2 < 2; ++t2)
; #pragma unroll
;                       for (int k2 = 0; k2 < 4; ++k2) { const bf16_t* qp = qh + ((th * 2 + t2) * 16 + fr) * 136 + k2 * 32 + fq * 4; qfr[t2][k2] = cat8(*(const bf16x4*)qp, *(const bf16x4*)(qp + 16)); }
;                   __builtin_amdgcn_sched_barrier(0);
; #pragma unroll
;                   for (int t2 = 0; t2 < 2; ++t2) oT[th * 2 + t2] = (f32x4){0.f, 0.f, 0.f, 0.f};
; #pragma unroll
;                   for (int k2 = 0; k2 < 4; ++k2)
; #pragma unroll
;                       for (int t2 = 0; t2 < 2; ++t2) oT[th * 2 + t2] = MFMA16(sa[k2], qfr[t2][k2], oT[th * 2 + t2]);
;                   __builtin_amdgcn_sched_barrier(0); } }
;             { bf16x8 vb[2];
; #pragma unroll
;               for (int ks = 0; ks < 2; ++ks) vb[ks] = *(const bf16x8*)(vt + (w * 16 + fr) * 72 + ks * 32 + fq * 8);
; #pragma unroll
;               for (int kh2 = 0; kh2 < 2; ++kh2) { bf16x8 kf[4][2]; f32x4 dv[4];
; #pragma unroll
;                   for (int k3 = 0; k3 < 4; ++k3) { dv[k3] = *(const f32x4*)(dl + (kh2 * 4 + k3) * 16 + fq * 4);
; #pragma unroll
;                       for (int ks = 0; ks < 2; ++ks) kf[k3][ks] = *(const bf16x8*)(kt + ((kh2 * 4 + k3) * 16 + fr) * 72 + ks * 32 + fq * 8); }
.LBB0_412:
	s_or_b64 exec, exec, s[16:17]
	s_and_b32 s19, s19, 1
	s_mul_i32 s16, s19, 0x4400
	v_add3_u32 v0, v125, s16, v180
	v_add_u32_e32 v152, 0x1000, v0
	ds_read2_b64 v[68:71], v0 offset1:4
	ds_read2_b64 v[184:187], v0 offset0:8 offset1:12
	ds_read2_b64 v[188:191], v0 offset0:16 offset1:20
	ds_read2_b64 v[192:195], v0 offset0:24 offset1:28
	ds_read2_b64 v[196:199], v152 offset0:32 offset1:36
	ds_read2_b64 v[200:203], v152 offset0:40 offset1:44
	ds_read2_b64 v[204:207], v152 offset0:48 offset1:52
	ds_read2_b64 v[216:219], v152 offset0:56 offset1:60
	v_cvt_pk_bf16_f32 v72, v36, v37
	v_cvt_pk_bf16_f32 v73, v38, v39
	v_cvt_pk_bf16_f32 v74, v40, v41
	v_cvt_pk_bf16_f32 v75, v42, v43
	v_cvt_pk_bf16_f32 v76, v44, v45
	v_cvt_pk_bf16_f32 v77, v46, v47
	v_cvt_pk_bf16_f32 v78, v48, v49
	v_cvt_pk_bf16_f32 v79, v50, v51
	v_cvt_pk_bf16_f32 v166, v56, v57
	v_cvt_pk_bf16_f32 v167, v58, v59
	v_cvt_pk_bf16_f32 v164, v52, v53
	v_cvt_pk_bf16_f32 v165, v54, v55
	v_cvt_pk_bf16_f32 v220, v60, v61
	v_cvt_pk_bf16_f32 v221, v62, v63
	v_cvt_pk_bf16_f32 v222, v64, v65
	v_cvt_pk_bf16_f32 v223, v66, v67
	s_waitcnt lgkmcnt(7)
	v_mfma_f32_16x16x32_bf16 v[68:71], v[72:75], v[68:71], 0
	s_waitcnt lgkmcnt(3)
	v_mfma_f32_16x16x32_bf16 v[196:199], v[72:75], v[196:199], 0
	v_mfma_f32_16x16x32_bf16 v[68:71], v[76:79], v[184:187], v[68:71]
	s_waitcnt lgkmcnt(2)
	v_mfma_f32_16x16x32_bf16 v[184:187], v[76:79], v[200:203], v[196:199]
	v_mfma_f32_16x16x32_bf16 v[68:71], v[164:167], v[188:191], v[68:71]
	s_waitcnt lgkmcnt(1)
	v_mfma_f32_16x16x32_bf16 v[184:187], v[164:167], v[204:207], v[184:187]
	v_mfma_f32_16x16x32_bf16 v[188:191], v[220:223], v[192:195], v[68:71]
	s_waitcnt lgkmcnt(0)
	v_mfma_f32_16x16x32_bf16 v[68:71], v[220:223], v[216:219], v[184:187]
	v_add_u32_e32 v152, 0x2000, v0
	v_add_u32_e32 v0, 0x3000, v0
	s_nop 2
	ds_read2_b64 v[184:187], v152 offset0:64 offset1:68
	ds_read2_b64 v[192:195], v152 offset0:72 offset1:76
	ds_read2_b64 v[196:199], v152 offset0:80 offset1:84
	ds_read2_b64 v[200:203], v152 offset0:88 offset1:92
	ds_read2_b64 v[204:207], v0 offset0:96 offset1:100
	ds_read2_b64 v[216:219], v0 offset0:104 offset1:108
	ds_read2_b64 v[224:227], v0 offset0:112 offset1:116
	ds_read2_b64 v[228:231], v0 offset0:120 offset1:124
	s_waitcnt lgkmcnt(7)
	v_mfma_f32_16x16x32_bf16 v[184:187], v[72:75], v[184:187], 0
	s_waitcnt lgkmcnt(3)
	v_mfma_f32_16x16x32_bf16 v[72:75], v[72:75], v[204:207], 0
	v_mfma_f32_16x16x32_bf16 v[184:187], v[76:79], v[192:195], v[184:187]
	s_waitcnt lgkmcnt(2)
	v_mfma_f32_16x16x32_bf16 v[72:75], v[76:79], v[216:219], v[72:75]
	v_mfma_f32_16x16x32_bf16 v[76:79], v[164:167], v[196:199], v[184:187]
	s_waitcnt lgkmcnt(1)
	v_mfma_f32_16x16x32_bf16 v[72:75], v[164:167], v[224:227], v[72:75]
	v_mfma_f32_16x16x32_bf16 v[76:79], v[220:223], v[200:203], v[76:79]
	s_waitcnt lgkmcnt(0)
	v_mfma_f32_16x16x32_bf16 v[72:75], v[220:223], v[228:231], v[72:75]
	s_mul_i32 s16, s19, 0x4800
	v_add_u32_e32 v0, s16, v170
	v_add3_u32 v152, v172, s16, v181
	ds_read_b128 v[164:167], v0
	ds_read_b128 v[184:187], v0 offset:64
	v_lshl_add_u32 v0, s19, 9, v171
	ds_read_b128 v[192:195], v152 offset:34816
	ds_read_b128 v[196:199], v152 offset:34880
	ds_read_b128 v[200:203], v0
	ds_read_b128 v[204:207], v0 offset:64
	ds_read_b128 v[216:219], v152 offset:37120
	ds_read_b128 v[220:223], v152 offset:37184
	ds_read_b128 v[224:227], v152 offset:39424
	ds_read_b128 v[228:231], v152 offset:39488
	ds_read_b128 v[232:235], v0 offset:128
	ds_read_b128 v[236:239], v0 offset:192
	ds_read_b128 v[240:243], v152 offset:41728
	ds_read_b128 v[244:247], v152 offset:41792
	s_waitcnt lgkmcnt(9)
; #define MFMA16(a, b, c) __builtin_amdgcn_mfma_f32_16x16x32_bf16((a), (b), (c), 0, 0, 0)
; __device__ __forceinline__ void hgrn_b(unsigned char* lds, const Params& p, int jl, const bf16_t* proj, bf16_t* mix, const float* dbuf, const bf16_t* scr, const float* useg, const float* dseg, int blk, int G, int tid) {
;     ...
;                   __builtin_amdgcn_sched_barrier(0);
; #pragma unroll
;                   for (int k3 = 0; k3 < 4; ++k3) S[kh2 * 4 + k3] = S[kh2 * 4 + k3] * dv[k3];
; #pragma unroll
;                   for (int ks = 0; ks < 2; ++ks)
; #pragma unroll
;                       for (int k3 = 0; k3 < 4; ++k3) S[kh2 * 4 + k3] = MFMA16(kf[k3][ks], vb[ks], S[kh2 * 4 + k3]);
;                   __builtin_amdgcn_sched_barrier(0); } }
; #pragma unroll
;             for (int tt = 0; tt < 4; ++tt) { float ss = 0.f;
; #pragma unroll
;                 for (int j = 0; j < 4; ++j) { const unsigned wv = oin[tt][j >> 1]; const float oi = __uint_as_float((j & 1) ? (wv & 0xffff0000u) : (wv << 16)); const float ov = oT[tt][j] + oi; oT[tt][j] = ov; ss += ov * ov; }
;                 ss += __shfl_xor(ss, 16); ss += __shfl_xor(ss, 32);
;                 if (fq == 0) PART[(tt * 16 + fr) * 8 + w] = ss; }
	v_mul_f32_e32 v36, v36, v200
	v_mul_f32_e32 v37, v37, v201
	v_mul_f32_e32 v38, v38, v202
	v_mul_f32_e32 v39, v39, v203
	s_waitcnt lgkmcnt(8)
	v_mul_f32_e32 v40, v40, v204
	v_mul_f32_e32 v41, v41, v205
	v_mul_f32_e32 v42, v42, v206
	v_mul_f32_e32 v43, v43, v207
	s_waitcnt lgkmcnt(3)
	v_mul_f32_e32 v44, v44, v232
	v_mul_f32_e32 v45, v45, v233
	v_mul_f32_e32 v46, v46, v234
	v_mul_f32_e32 v47, v47, v235
	s_waitcnt lgkmcnt(2)
	v_mul_f32_e32 v48, v48, v236
	v_mul_f32_e32 v49, v49, v237
	v_mul_f32_e32 v50, v50, v238
	v_mul_f32_e32 v51, v51, v239
	v_mfma_f32_16x16x32_bf16 v[36:39], v[192:195], v[164:167], v[36:39]
	v_mfma_f32_16x16x32_bf16 v[40:43], v[216:219], v[164:167], v[40:43]
	v_mfma_f32_16x16x32_bf16 v[44:47], v[224:227], v[164:167], v[44:47]
	s_waitcnt lgkmcnt(1)
	v_mfma_f32_16x16x32_bf16 v[48:51], v[240:243], v[164:167], v[48:51]
	v_mfma_f32_16x16x32_bf16 v[36:39], v[196:199], v[184:187], v[36:39]
	v_mfma_f32_16x16x32_bf16 v[40:43], v[220:223], v[184:187], v[40:43]
	v_mfma_f32_16x16x32_bf16 v[44:47], v[228:231], v[184:187], v[44:47]
	s_waitcnt lgkmcnt(0)
	v_mfma_f32_16x16x32_bf16 v[48:51], v[244:247], v[184:187], v[48:51]
	ds_read_b128 v[192:195], v152 offset:44032
	ds_read_b128 v[196:199], v152 offset:44096
	ds_read_b128 v[200:203], v0 offset:256
	ds_read_b128 v[204:207], v0 offset:320
	ds_read_b128 v[216:219], v152 offset:46336
	ds_read_b128 v[220:223], v152 offset:46400
	ds_read_b128 v[224:227], v152 offset:48640
	ds_read_b128 v[228:231], v152 offset:48704
	ds_read_b128 v[232:235], v0 offset:384
	ds_read_b128 v[236:239], v0 offset:448
	ds_read_b128 v[240:243], v152 offset:50944
	ds_read_b128 v[244:247], v152 offset:51008
	s_waitcnt lgkmcnt(9)
	v_mul_f32_e32 v52, v52, v200
	v_mul_f32_e32 v53, v53, v201
	v_mul_f32_e32 v54, v54, v202
	v_mul_f32_e32 v55, v55, v203
	s_waitcnt lgkmcnt(8)
	v_mul_f32_e32 v56, v56, v204
	v_mul_f32_e32 v57, v57, v205
	v_mul_f32_e32 v58, v58, v206
	v_mul_f32_e32 v59, v59, v207
	s_waitcnt lgkmcnt(3)
	v_mul_f32_e32 v60, v60, v232
	v_mul_f32_e32 v61, v61, v233
	v_mul_f32_e32 v62, v62, v234
	v_mul_f32_e32 v63, v63, v235
	s_waitcnt lgkmcnt(2)
	v_mul_f32_e32 v64, v64, v236
	v_mul_f32_e32 v65, v65, v237
	v_mul_f32_e32 v66, v66, v238
	v_mul_f32_e32 v67, v67, v239
	v_mfma_f32_16x16x32_bf16 v[52:55], v[192:195], v[164:167], v[52:55]
	v_mfma_f32_16x16x32_bf16 v[56:59], v[216:219], v[164:167], v[56:59]
	v_mfma_f32_16x16x32_bf16 v[60:63], v[224:227], v[164:167], v[60:63]
	s_waitcnt lgkmcnt(1)
	v_mfma_f32_16x16x32_bf16 v[64:67], v[240:243], v[164:167], v[64:67]
	v_mfma_f32_16x16x32_bf16 v[52:55], v[196:199], v[184:187], v[52:55]
	v_mfma_f32_16x16x32_bf16 v[56:59], v[220:223], v[184:187], v[56:59]
	v_mfma_f32_16x16x32_bf16 v[60:63], v[228:231], v[184:187], v[60:63]
	s_waitcnt lgkmcnt(0)
	v_mfma_f32_16x16x32_bf16 v[64:67], v[244:247], v[184:187], v[64:67]
	s_waitcnt vmcnt(3)
	v_lshlrev_b32_e32 v152, 16, v162
	v_and_b32_e32 v153, 0xffff0000, v162
	v_pk_add_f32 v[166:167], v[188:189], v[152:153]
	v_lshlrev_b32_e32 v162, 16, v163
	v_and_b32_e32 v163, 0xffff0000, v163
	v_pk_mul_f32 v[152:153], v[166:167], v[166:167]
	v_pk_add_f32 v[168:169], v[190:191], v[162:163]
	v_add_f32_e32 v0, v152, v153
	v_pk_mul_f32 v[162:163], v[168:169], v[168:169]
	s_nop 0
	v_add_f32_e32 v0, v162, v0
	v_add_f32_e32 v0, v163, v0
	v_mov_b32_e32 v152, v0
	s_nop 1
	v_permlane16_swap_b32_e32 v152, v0
	v_add_f32_e32 v0, v0, v152
	v_mov_b32_e32 v162, v0
	s_nop 1
	v_permlane32_swap_b32_e32 v162, v0
	v_add_f32_e32 v0, v0, v162
	s_and_saveexec_b64 s[16:17], s[4:5]
	s_cbranch_execz .LBB0_414
	ds_write_b32 v176, v0
